# v38 plus S5 stage-3: mirror the wave to row-group map on odd groups so all four waves run the same number of k-steps
# speedup vs baseline: 1.0085x; 1.0074x over previous
; DI void s5_stage3_item(const Params& P, int l, int it, u16* hs, int wave, int lane) {
;     ...
;   for (int gi = 0; gi < 8; ++gi) {
;     const int jg = wave + 4 * (gi >> 1);
;     const int th = gi & 1;
;     f32x4 acc[4][2]; zero_acc(acc);
;     wgemm<4, 2>(acc, 2 * jg + 2,
;                 [&](int i, int ks) { const int j = 4 * jg + i, ii = 2 * ks + (q >> 1); const int d = j - ii;
;                                      return (d >= 0) ? ld8(Kt + ((size_t)d * 16 + jn) * 16 + (q & 1) * 8) : zf; },
.LBB0_837:
	s_lshl_b32 s2, s15, 1
	s_and_b32 s17, s2, 12
	s_sub_i32 s3, 3, s12
	s_bitcmp1_b32 s15, 1
	s_cselect_b32 s3, s3, s12
	s_add_i32 s17, s17, s3
	s_lshl_b32 s2, s17, 2
	v_sub_u32_e32 v0, s2, v106
	v_cmp_lt_i32_e32 vcc, -1, v0
	v_mov_b32_e32 v2, 0
	v_mov_b32_e32 v6, 0
	v_mov_b32_e32 v7, 0
	v_mov_b32_e32 v8, 0
	v_mov_b32_e32 v9, 0
	s_and_saveexec_b64 s[4:5], vcc
	s_cbranch_execz .LBB0_839
	v_lshlrev_b64 v[4:5], 9, v[0:1]
	v_lshl_add_u64 v[4:5], v[100:101], 0, v[4:5]
	global_load_dwordx4 v[6:9], v[4:5], off

; DI void s5_stage3_item(const Params& P, int l, int it, u16* hs, int wave, int lane) {
;     ...
;     const int th = gi & 1;
;     f32x4 acc[4][2]; zero_acc(acc);
;     wgemm<4, 2>(acc, 2 * jg + 2,
;                 [&](int i, int ks) { const int j = 4 * jg + i, ii = 2 * ks + (q >> 1); const int d = j - ii;
;                                      return (d >= 0) ? ld8(Kt + ((size_t)d * 16 + jn) * 16 + (q & 1) * 8) : zf; },
;                 [&](int jt, int ks) { return ld8(up + ((size_t)(2 * th + jt) * 16 * 64 + 2 * ks) * DINP); });
;     wgemm<4, 2>(acc, 4,
.LBB0_853:
	s_or_b64 exec, exec, s[10:11]
	s_and_b32 s16, s15, 1
	s_cmp_lt_i32 s17, 0
	s_cbranch_scc1 .LBB0_835
	s_lshl_b32 s3, s16, 1
	s_or_b32 s5, s3, 1
	s_mul_i32 s10, s5, 0x500000
	s_mov_b32 s11, s35
	v_lshl_add_u64 v[14:15], v[90:91], 0, s[10:11]
	v_add_co_u32_e32 v16, vcc, 0x3000, v14
	s_mul_i32 s10, s16, 0xa00000
	s_nop 0
	v_addc_co_u32_e32 v17, vcc, 0, v15, vcc
	v_lshl_add_u64 v[18:19], v[90:91], 0, s[10:11]
	global_load_dwordx4 v[74:77], v[16:17], off offset:336
	global_load_dwordx4 v[62:65], v[14:15], off offset:2384
	v_add_co_u32_e32 v14, vcc, 0x3000, v18
	s_lshl_b32 s3, s14, 1
	s_nop 0
	v_addc_co_u32_e32 v15, vcc, 0, v19, vcc
	global_load_dwordx4 v[66:69], v[18:19], off offset:2384
	global_load_dwordx4 v[78:81], v[14:15], off offset:336
	s_and_b32 s3, s3, -8
	s_lshl_b32 s9, s17, 1
	v_mov_b32_e32 v14, 0
	s_lshl_b32 s3, s17, 1
	s_lshl_b32 s5, s5, 10
	s_lshl_b32 s7, s16, 11
	s_or_b32 s9, s9, 1
	s_mov_b32 s17, -2
	v_mov_b32_e32 v15, v14
	v_mov_b32_e32 v16, v14
	v_mov_b32_e32 v17, v14
	v_mov_b32_e32 v18, v14
	v_mov_b32_e32 v19, v14
	v_mov_b32_e32 v20, v14
	v_mov_b32_e32 v21, v14
	v_mov_b32_e32 v22, v14
	v_mov_b32_e32 v23, v14
	v_mov_b32_e32 v24, v14
	v_mov_b32_e32 v25, v14
	s_waitcnt vmcnt(15)
	v_mov_b32_e32 v26, v14
	v_mov_b32_e32 v27, v14
	v_mov_b32_e32 v28, v14
	v_mov_b32_e32 v29, v14
	s_waitcnt vmcnt(14)
	v_mov_b32_e32 v30, v14
	v_mov_b32_e32 v31, v14
	v_mov_b32_e32 v32, v14
	v_mov_b32_e32 v33, v14
	v_mov_b32_e32 v38, v14
	v_mov_b32_e32 v39, v14
	v_mov_b32_e32 v40, v14
	v_mov_b32_e32 v41, v14
	s_waitcnt vmcnt(13)
	v_mov_b32_e32 v42, v14
	v_mov_b32_e32 v43, v14
	v_mov_b32_e32 v44, v14
	v_mov_b32_e32 v45, v14
	s_waitcnt vmcnt(12)
	v_mov_b32_e32 v46, v14
	v_mov_b32_e32 v47, v14
	v_mov_b32_e32 v48, v14
	v_mov_b32_e32 v49, v14
